# speedup vs baseline: 1.0061x; 1.0021x over previous
; template <int NT, int BM, int BN, bool PLAIN, int NSTAGE, bool EPI_LDS>
; __device__ __forceinline__ void gemm_tile(const Params& p, const GemmDesc& g, bf16_t* lds, const int tid) {
;     ...
;   const int r0 = tid >> 3, c0 = tid & 7;
;   unsigned aoff[PLAIN ? 1 : NA];
;   const char* abase = (const char*)g.A;
;   if (PLAIN) {
;     abase = (const char*)(g.A + (long)m0 * g.lda_lo);
;     aoff[0] = (unsigned)((r0 * (int)g.lda_lo + c0 * 8) * 2);
;   } else {
; #pragma unroll
;     for (int i = 0; i < NA; ++i) {
;       int ra = m0 + r0 + RP * i;
;       int rlo = ra & g.rmask; rlo = rlo < g.rclamp ? rlo : g.rclamp;
;       aoff[i] = (unsigned)(((long)rlo * g.lda_lo + (long)(ra >> g.rshift) * g.lda_hi + c0 * 8) * 2);
;     }
;   }
;   const char* bbase = (const char*)(g.Bt + (long)n0 * g.ldb);
;   const unsigned boff = (unsigned)((r0 * (int)g.ldb + c0 * 8) * 2);
;   const long astepP = (long)RP * g.lda_lo * 2, bstepP = (long)RP * g.ldb * 2;
;   u32x4 ra4[NA], rb4[NB];
;   f32x4 acc[MI][NI];
; #pragma unroll
;   for (int i = 0; i < MI; ++i)
; #pragma unroll
;     for (int j = 0; j < NI; ++j) acc[i][j] = f32x4{0.f, 0.f, 0.f, 0.f};
;   const int nk = g.K >> 6;
;     ...
;   constexpr int STAGE_BYTES = (BM + BN) * 128;
;   char* const ldsb = (char*)lds;
;   const unsigned woff = (unsigned)(((r0 >> 4) * 2 + (c0 >> 2)) * 1024 + (((((r0 & 15) ^ (c0 >> 2)) * 64) + (c0 & 3) * 16) ^ (((r0 & 15) >> 3) << 5)));
;   const unsigned roff = (unsigned)(((fr * 64) + fq * 16) ^ ((fr >> 3) << 5));
;     ...
;     GLOAD(0)
;     __syncthreads();
;     LWRITE(0)
;     if (nk > 1) GLOAD(1)
;     __syncthreads();
.Lmy_noprio:
	s_and_b32 s62, s57, 3
	s_lshl_b32 s62, s62, 6
	s_add_i32 s59, s59, s62
	s_mul_i32 s59, s59, s58
	s_lshl_b32 s58, s58, 1
	s_lshl_b32 s59, s59, 1
	s_add_u32 s60, s60, s59
	s_addc_u32 s61, s61, 0
	v_mul_lo_u32 v3, v3, s58
	s_lshl_b32 s62, s58, 3
	v_add_u32_e32 v162, v3, v4
	v_add3_u32 v163, v3, v5, s62
	s_lshl_b32 s62, s58, 4
	v_add_u32_e32 v164, s62, v162
	v_add_u32_e32 v165, s62, v163
	v_add_u32_e32 v166, s62, v164
	v_add_u32_e32 v167, s62, v165
	v_add_u32_e32 v168, s62, v166
	v_add_u32_e32 v169, s62, v167
	s_lshl_b32 s57, s57, 13
	s_barrier
	s_mov_b32 m0, s57
	s_nop 0
	global_load_lds_dwordx4 v162, s[60:61]
	s_add_u32 m0, m0, 0x400
	s_nop 0
	global_load_lds_dwordx4 v163, s[60:61]
	s_add_u32 m0, m0, 0x400
	s_nop 0
	global_load_lds_dwordx4 v164, s[60:61]
	s_add_u32 m0, m0, 0x400
	s_nop 0
	global_load_lds_dwordx4 v165, s[60:61]
	s_add_u32 m0, m0, 0x400
	s_nop 0
	global_load_lds_dwordx4 v166, s[60:61]
	s_add_u32 m0, m0, 0x400
	s_nop 0
	global_load_lds_dwordx4 v167, s[60:61]
	s_add_u32 m0, m0, 0x400
	s_nop 0
	global_load_lds_dwordx4 v168, s[60:61]
	s_add_u32 m0, m0, 0x400
	s_nop 0
	global_load_lds_dwordx4 v169, s[60:61]
	s_add_u32 s60, s60, 0x80
	s_addc_u32 s61, s61, 0
	s_add_u32 m0, s57, 0x10000
	s_nop 0
	global_load_lds_dwordx4 v162, s[60:61]
	s_add_u32 m0, m0, 0x400
	s_nop 0
	global_load_lds_dwordx4 v163, s[60:61]
	s_add_u32 m0, m0, 0x400
	s_nop 0
	global_load_lds_dwordx4 v164, s[60:61]
	s_add_u32 m0, m0, 0x400
	s_nop 0
	global_load_lds_dwordx4 v165, s[60:61]
	v_mov_b32_e32 v110, 0
	v_mov_b32_e32 v111, v110
	v_mov_b32_e32 v112, v110
	v_mov_b32_e32 v113, v110
	v_mov_b32_e32 v90, v110
	v_mov_b32_e32 v91, v110
	v_mov_b32_e32 v92, v110
	v_mov_b32_e32 v93, v110
	v_mov_b32_e32 v40, v110
	v_mov_b32_e32 v41, v110
	v_mov_b32_e32 v42, v110
	v_mov_b32_e32 v43, v110
	v_mov_b32_e32 v44, v110
	v_mov_b32_e32 v45, v110
	v_mov_b32_e32 v46, v110
	v_mov_b32_e32 v47, v110
	v_mov_b32_e32 v48, v110
	v_mov_b32_e32 v49, v110
	v_mov_b32_e32 v50, v110
	v_mov_b32_e32 v51, v110
	v_mov_b32_e32 v52, v110
	v_mov_b32_e32 v53, v110
	v_mov_b32_e32 v54, v110
	v_mov_b32_e32 v55, v110
	v_mov_b32_e32 v56, v110
	v_mov_b32_e32 v57, v110
	v_mov_b32_e32 v58, v110
	v_mov_b32_e32 v59, v110
	v_mov_b32_e32 v60, v110
	v_mov_b32_e32 v61, v110
	v_mov_b32_e32 v62, v110
	v_mov_b32_e32 v63, v110
	v_mov_b32_e32 v64, v110
	v_mov_b32_e32 v65, v110
	v_mov_b32_e32 v66, v110
	v_mov_b32_e32 v67, v110
	v_mov_b32_e32 v68, v110
	v_mov_b32_e32 v69, v110
	v_mov_b32_e32 v70, v110
	v_mov_b32_e32 v71, v110
	v_mov_b32_e32 v72, v110
	v_mov_b32_e32 v73, v110
	v_mov_b32_e32 v74, v110
	v_mov_b32_e32 v75, v110
	v_mov_b32_e32 v76, v110
	v_mov_b32_e32 v34, v110
	v_mov_b32_e32 v35, v110
	v_mov_b32_e32 v36, v110
	v_mov_b32_e32 v37, v110
	v_mov_b32_e32 v38, v110
	v_mov_b32_e32 v39, v110
	v_mov_b32_e32 v77, v110
	v_mov_b32_e32 v78, v110
	v_mov_b32_e32 v79, v110
	v_mov_b32_e32 v80, v110
	v_mov_b32_e32 v81, v110
	v_mov_b32_e32 v82, v110
	v_mov_b32_e32 v83, v110
	v_mov_b32_e32 v84, v110
	v_mov_b32_e32 v85, v110
	v_mov_b32_e32 v86, v110
	v_mov_b32_e32 v87, v110
	v_mov_b32_e32 v88, v110
	v_mov_b32_e32 v89, v110
	v_mov_b32_e32 v94, v110
	v_mov_b32_e32 v95, v110
	v_mov_b32_e32 v96, v110
	v_mov_b32_e32 v97, v110
	v_mov_b32_e32 v98, v110
	v_mov_b32_e32 v99, v110
	v_mov_b32_e32 v100, v110
	v_mov_b32_e32 v101, v110
	v_mov_b32_e32 v102, v110
	v_mov_b32_e32 v103, v110
	v_mov_b32_e32 v104, v110
	v_mov_b32_e32 v105, v110
	v_mov_b32_e32 v106, v110
	v_mov_b32_e32 v107, v110
	v_mov_b32_e32 v108, v110
	v_mov_b32_e32 v109, v110
	v_mov_b32_e32 v114, v110
	v_mov_b32_e32 v115, v110
	v_mov_b32_e32 v116, v110
	v_mov_b32_e32 v117, v110
	v_mov_b32_e32 v118, v110
	v_mov_b32_e32 v119, v110
	v_mov_b32_e32 v120, v110
	v_mov_b32_e32 v121, v110
	v_mov_b32_e32 v122, v110
	v_mov_b32_e32 v123, v110
	v_mov_b32_e32 v124, v110
	v_mov_b32_e32 v125, v110
	v_mov_b32_e32 v126, v110
	v_mov_b32_e32 v127, v110
	v_mov_b32_e32 v128, v110
	v_mov_b32_e32 v129, v110
	v_mov_b32_e32 v130, v110
	v_mov_b32_e32 v131, v110
	v_mov_b32_e32 v132, v110
	v_mov_b32_e32 v133, v110
	v_mov_b32_e32 v134, v110
	v_mov_b32_e32 v135, v110
	v_mov_b32_e32 v136, v110
	v_mov_b32_e32 v137, v110
	v_mov_b32_e32 v138, v110
	v_mov_b32_e32 v139, v110
	v_mov_b32_e32 v140, v110
	v_mov_b32_e32 v141, v110
	v_mov_b32_e32 v142, v110
	v_mov_b32_e32 v143, v110
	v_mov_b32_e32 v144, v110
	v_mov_b32_e32 v145, v110
	v_mov_b32_e32 v146, v110
	v_mov_b32_e32 v147, v110
	v_mov_b32_e32 v148, v110
	v_mov_b32_e32 v149, v110
	v_mov_b32_e32 v150, v110
	v_mov_b32_e32 v151, v110
	v_mov_b32_e32 v152, v110
	v_mov_b32_e32 v153, v110
	v_mov_b32_e32 v154, v110
	v_mov_b32_e32 v155, v110
	v_mov_b32_e32 v156, v110
	v_mov_b32_e32 v157, v110
	v_mov_b32_e32 v158, v110
	v_mov_b32_e32 v159, v110
	v_mov_b32_e32 v160, v110
	v_mov_b32_e32 v161, v110
	s_add_i32 s3, s23, -2
	s_mov_b32 s26, 0
	s_mov_b32 s27, s3
	s_waitcnt vmcnt(4)
	s_barrier
	v_add_u32_e32 v19, v180, v184
	v_add_u32_e32 v18, v180, v183
	ds_read_b128 v[2:5], v19 offset:32768
	ds_read_b128 v[6:9], v19 offset:34816
	ds_read_b128 v[10:13], v19 offset:36864
	ds_read_b128 v[14:17], v19 offset:38912
	ds_read_b128 v[202:205], v18
	ds_read_b128 v[206:209], v18 offset:2048
	ds_read_b128 v[226:229], v18 offset:4096
	s_and_b32 s28, s26, 0x10000
	s_xor_b32 s29, s28, 0x10000
	s_add_u32 m0, s29, s57
	s_add_u32 m0, m0, 0x1000
	v_or_b32_e32 v0, s28, v180
	v_add_u32_e32 v218, v0, v184
	v_add_u32_e32 v0, v0, v183
	.p2align 6
; template <int NT, int BM, int BN, bool PLAIN, int NSTAGE, bool EPI_LDS>
; __device__ __forceinline__ void gemm_tile(const Params& p, const GemmDesc& g, bf16_t* lds, const int tid) {
;     ...
;       for (; kt + 2 < nk; ++kt) {
;         const int cur = kt & 1;
;         COMPUTE_X(cur, 1, 1, kt + 2)
;         __syncthreads();
;       }
.LBB0_897:
	s_waitcnt lgkmcnt(2)
	v_mfma_f32_16x16x32_bf16 v[158:161], v[2:5], v[202:205], v[158:161]
	global_load_lds_dwordx4 v166, s[60:61]
	s_add_u32 m0, m0, 0x400
	v_add_u32_e32 v218, v218, v181
	s_add_i32 s27, s27, -1
	v_mfma_f32_16x16x32_bf16 v[154:157], v[6:9], v[202:205], v[154:157]
	s_add_i32 s26, s26, 0x10000
	v_mfma_f32_16x16x32_bf16 v[150:153], v[10:13], v[202:205], v[150:153]
	global_load_lds_dwordx4 v167, s[60:61]
	s_add_u32 m0, m0, 0x400
	v_mfma_f32_16x16x32_bf16 v[146:149], v[14:17], v[202:205], v[146:149]
	ds_read_b128 v[202:205], v0 offset:6144
	s_waitcnt lgkmcnt(2)
	v_mfma_f32_16x16x32_bf16 v[142:145], v[2:5], v[206:209], v[142:145]
	global_load_lds_dwordx4 v168, s[60:61]
	s_add_u32 m0, m0, 0x400
	v_mfma_f32_16x16x32_bf16 v[138:141], v[6:9], v[206:209], v[138:141]
	v_mfma_f32_16x16x32_bf16 v[134:137], v[10:13], v[206:209], v[134:137]
	global_load_lds_dwordx4 v169, s[60:61]
	s_add_u32 s60, s60, 0x80
	s_addc_u32 s61, s61, 0
	v_mfma_f32_16x16x32_bf16 v[130:133], v[14:17], v[206:209], v[130:133]
	ds_read_b128 v[206:209], v0 offset:8192
	s_waitcnt lgkmcnt(2)
	v_mfma_f32_16x16x32_bf16 v[126:129], v[2:5], v[226:229], v[126:129]
	v_mfma_f32_16x16x32_bf16 v[122:125], v[6:9], v[226:229], v[122:125]
	v_mfma_f32_16x16x32_bf16 v[118:121], v[10:13], v[226:229], v[118:121]
	v_mfma_f32_16x16x32_bf16 v[114:117], v[14:17], v[226:229], v[114:117]
	ds_read_b128 v[226:229], v0 offset:10240
	s_waitcnt lgkmcnt(2)
	v_mfma_f32_16x16x32_bf16 v[106:109], v[2:5], v[202:205], v[106:109]
	v_mfma_f32_16x16x32_bf16 v[102:105], v[6:9], v[202:205], v[102:105]
	v_mfma_f32_16x16x32_bf16 v[98:101], v[10:13], v[202:205], v[98:101]
	v_mfma_f32_16x16x32_bf16 v[94:97], v[14:17], v[202:205], v[94:97]
	ds_read_b128 v[202:205], v0 offset:12288
	ds_read_b128 v[230:233], v218 offset:32768
	s_waitcnt lgkmcnt(3)
	v_mfma_f32_16x16x32_bf16 v[86:89], v[2:5], v[206:209], v[86:89]
	v_mfma_f32_16x16x32_bf16 v[82:85], v[6:9], v[206:209], v[82:85]
	v_mfma_f32_16x16x32_bf16 v[78:81], v[10:13], v[206:209], v[78:81]
	v_mfma_f32_16x16x32_bf16 v[74:77], v[14:17], v[206:209], v[74:77]
	ds_read_b128 v[206:209], v0 offset:14336
	ds_read_b128 v[234:237], v218 offset:34816
	v_add_u32_e32 v0, v0, v181
	s_waitcnt lgkmcnt(4)
	v_mfma_f32_16x16x32_bf16 v[70:73], v[2:5], v[226:229], v[70:73]
	v_mfma_f32_16x16x32_bf16 v[66:69], v[6:9], v[226:229], v[66:69]
	v_mfma_f32_16x16x32_bf16 v[62:65], v[10:13], v[226:229], v[62:65]
	v_mfma_f32_16x16x32_bf16 v[58:61], v[14:17], v[226:229], v[58:61]
	ds_read_b128 v[226:229], v0 offset:0
	ds_read_b128 v[238:241], v218 offset:36864
	s_waitcnt lgkmcnt(5)
	v_mfma_f32_16x16x32_bf16 v[54:57], v[2:5], v[202:205], v[54:57]
	v_mfma_f32_16x16x32_bf16 v[50:53], v[6:9], v[202:205], v[50:53]
	v_mfma_f32_16x16x32_bf16 v[46:49], v[10:13], v[202:205], v[46:49]
	v_mfma_f32_16x16x32_bf16 v[42:45], v[14:17], v[202:205], v[42:45]
	ds_read_b128 v[202:205], v0 offset:2048
	ds_read_b128 v[242:245], v218 offset:38912
	s_waitcnt lgkmcnt(5)
	v_mfma_f32_16x16x32_bf16 v[38:41], v[2:5], v[206:209], v[38:41]
	v_mfma_f32_16x16x32_bf16 v[34:37], v[6:9], v[206:209], v[34:37]
	v_mfma_f32_16x16x32_bf16 v[90:93], v[10:13], v[206:209], v[90:93]
	v_mfma_f32_16x16x32_bf16 v[110:113], v[14:17], v[206:209], v[110:113]
	ds_read_b128 v[186:189], v0 offset:4096
	s_waitcnt lgkmcnt(4)
	v_mfma_f32_16x16x32_bf16 v[158:161], v[230:233], v[226:229], v[158:161]
	v_mfma_f32_16x16x32_bf16 v[154:157], v[234:237], v[226:229], v[154:157]
	s_waitcnt lgkmcnt(3)
	v_mfma_f32_16x16x32_bf16 v[150:153], v[238:241], v[226:229], v[150:153]
	s_waitcnt lgkmcnt(1)
	v_mfma_f32_16x16x32_bf16 v[146:149], v[242:245], v[226:229], v[146:149]
	ds_read_b128 v[190:193], v0 offset:6144
	v_mfma_f32_16x16x32_bf16 v[142:145], v[230:233], v[202:205], v[142:145]
	v_mfma_f32_16x16x32_bf16 v[138:141], v[234:237], v[202:205], v[138:141]
	v_mfma_f32_16x16x32_bf16 v[134:137], v[238:241], v[202:205], v[134:137]
	v_mfma_f32_16x16x32_bf16 v[130:133], v[242:245], v[202:205], v[130:133]
	ds_read_b128 v[194:197], v0 offset:8192
	s_waitcnt lgkmcnt(2)
	v_mfma_f32_16x16x32_bf16 v[126:129], v[230:233], v[186:189], v[126:129]
	v_mfma_f32_16x16x32_bf16 v[122:125], v[234:237], v[186:189], v[122:125]
	v_mfma_f32_16x16x32_bf16 v[118:121], v[238:241], v[186:189], v[118:121]
	v_mfma_f32_16x16x32_bf16 v[114:117], v[242:245], v[186:189], v[114:117]
	ds_read_b128 v[186:189], v0 offset:10240
	s_waitcnt lgkmcnt(2)
	v_mfma_f32_16x16x32_bf16 v[106:109], v[230:233], v[190:193], v[106:109]
	v_mfma_f32_16x16x32_bf16 v[102:105], v[234:237], v[190:193], v[102:105]
	v_mfma_f32_16x16x32_bf16 v[98:101], v[238:241], v[190:193], v[98:101]
	v_mfma_f32_16x16x32_bf16 v[94:97], v[242:245], v[190:193], v[94:97]
	ds_read_b128 v[190:193], v0 offset:12288
	s_waitcnt lgkmcnt(2)
	v_mfma_f32_16x16x32_bf16 v[86:89], v[230:233], v[194:197], v[86:89]
	v_mfma_f32_16x16x32_bf16 v[82:85], v[234:237], v[194:197], v[82:85]
	v_mfma_f32_16x16x32_bf16 v[78:81], v[238:241], v[194:197], v[78:81]
	v_mfma_f32_16x16x32_bf16 v[74:77], v[242:245], v[194:197], v[74:77]
	ds_read_b128 v[194:197], v0 offset:14336
	s_waitcnt lgkmcnt(2)
	v_mfma_f32_16x16x32_bf16 v[70:73], v[230:233], v[186:189], v[70:73]
	v_mfma_f32_16x16x32_bf16 v[66:69], v[234:237], v[186:189], v[66:69]
	v_mfma_f32_16x16x32_bf16 v[62:65], v[238:241], v[186:189], v[62:65]
	v_mfma_f32_16x16x32_bf16 v[58:61], v[242:245], v[186:189], v[58:61]
	s_waitcnt vmcnt(0) lgkmcnt(0)
	s_barrier
; template <int NT, int BM, int BN, bool PLAIN, int NSTAGE, bool EPI_LDS>
; __device__ __forceinline__ void gemm_tile(const Params& p, const GemmDesc& g, bf16_t* lds, const int tid) {
;     ...
;     if (PLAIN) {
;       int kt = 0;
;       for (; kt + 2 < nk; ++kt) {
;         const int cur = kt & 1;
;         COMPUTE_X(cur, 1, 1, kt + 2)
;         __syncthreads();
;       }
;       if (kt + 1 < nk) {
;         const int cur = kt & 1;
;         COMPUTE_X(cur, 1, 0, 0)
;         __syncthreads();
;         ++kt;
	s_xor_b32 s29, s28, 0x10000
	v_or_b32_e32 v18, s29, v180
	v_add_u32_e32 v19, v18, v184
	v_add_u32_e32 v18, v18, v183
	ds_read_b128 v[2:5], v19 offset:32768
	ds_read_b128 v[6:9], v19 offset:34816
	ds_read_b128 v[10:13], v19 offset:36864
	ds_read_b128 v[14:17], v19 offset:38912
	ds_read_b128 v[202:205], v18
	ds_read_b128 v[206:209], v18 offset:2048
	ds_read_b128 v[226:229], v18 offset:4096
	s_add_u32 m0, s28, s57
	v_mfma_f32_16x16x32_bf16 v[54:57], v[230:233], v[190:193], v[54:57]
	global_load_lds_dwordx4 v162, s[60:61]
	s_add_u32 m0, m0, 0x400
	v_mfma_f32_16x16x32_bf16 v[50:53], v[234:237], v[190:193], v[50:53]
	v_mfma_f32_16x16x32_bf16 v[46:49], v[238:241], v[190:193], v[46:49]
	global_load_lds_dwordx4 v163, s[60:61]
	s_add_u32 m0, m0, 0x400
	v_mfma_f32_16x16x32_bf16 v[42:45], v[242:245], v[190:193], v[42:45]
	v_mfma_f32_16x16x32_bf16 v[38:41], v[230:233], v[194:197], v[38:41]
	global_load_lds_dwordx4 v164, s[60:61]
	s_add_u32 m0, m0, 0x400
	v_mfma_f32_16x16x32_bf16 v[34:37], v[234:237], v[194:197], v[34:37]
	v_mfma_f32_16x16x32_bf16 v[90:93], v[238:241], v[194:197], v[90:93]
	global_load_lds_dwordx4 v165, s[60:61]
	v_mfma_f32_16x16x32_bf16 v[110:113], v[242:245], v[194:197], v[110:113]
	s_and_b32 s28, s26, 0x10000
	s_xor_b32 s29, s28, 0x10000
	s_add_u32 m0, s29, s57
	s_add_u32 m0, m0, 0x1000
	v_or_b32_e32 v0, s28, v180
	v_add_u32_e32 v218, v0, v184
	v_add_u32_e32 v0, v0, v183
	s_cmp_lg_u32 s27, 0
	s_cbranch_scc1 .LBB0_897
	s_setprio 0
	s_lshl_b32 s3, s3, 16
	s_and_b32 s3, s3, 0x10000
	s_xor_b32 s29, s3, 0x10000
	s_add_u32 m0, s29, s57
	s_add_u32 m0, m0, 0x1000
	s_nop 0
	global_load_lds_dwordx4 v166, s[60:61]
	s_add_u32 m0, m0, 0x400
	s_nop 0
	global_load_lds_dwordx4 v167, s[60:61]
	s_add_u32 m0, m0, 0x400
	s_nop 0
	global_load_lds_dwordx4 v168, s[60:61]
	s_add_u32 m0, m0, 0x400
	s_nop 0
	global_load_lds_dwordx4 v169, s[60:61]
	v_or_b32_e32 v0, s3, v180
	v_add_u32_e32 v198, v0, v184
	ds_read_b128 v[162:165], v198 offset:32768
	ds_read_b128 v[166:169], v198 offset:34816
	ds_read_b128 v[170:173], v198 offset:36864
	ds_read_b128 v[186:189], v198 offset:38912
	v_add_u32_e32 v0, v0, v183
	ds_read_b128 v[174:177], v0
	ds_read_b128 v[190:193], v0 offset:2048
	ds_read_b128 v[194:197], v0 offset:4096
	s_waitcnt lgkmcnt(2)
	v_mfma_f32_16x16x32_bf16 v[30:33], v[162:165], v[174:177], v[158:161]
	s_not_b32 s3, s23
	s_lshl_b32 s3, s3, 16
	s_and_b32 s3, s3, 0x10000
	v_mfma_f32_16x16x32_bf16 v[154:157], v[166:169], v[174:177], v[154:157]
	s_cmp_lg_u32 s56, 9
	s_cselect_b64 s[26:27], -1, 0
	s_mov_b32 s24, s41
	v_mfma_f32_16x16x32_bf16 v[150:153], v[170:173], v[174:177], v[150:153]
	s_mov_b32 s23, s42
	s_mov_b64 s[28:29], -1
	s_and_b64 vcc, exec, s[26:27]
	v_mfma_f32_16x16x32_bf16 v[146:149], v[186:189], v[174:177], v[146:149]
	ds_read_b128 v[158:161], v0 offset:6144
	v_add_u32_e32 v174, v198, v181
	s_waitcnt lgkmcnt(2)
	v_mfma_f32_16x16x32_bf16 v[26:29], v[162:165], v[190:193], v[142:145]
	v_mfma_f32_16x16x32_bf16 v[138:141], v[166:169], v[190:193], v[138:141]
	v_mfma_f32_16x16x32_bf16 v[134:137], v[170:173], v[190:193], v[134:137]
	v_mfma_f32_16x16x32_bf16 v[130:133], v[186:189], v[190:193], v[130:133]
	ds_read_b128 v[142:145], v0 offset:8192
	s_waitcnt lgkmcnt(2)
	v_mfma_f32_16x16x32_bf16 v[22:25], v[162:165], v[194:197], v[126:129]
	v_mfma_f32_16x16x32_bf16 v[122:125], v[166:169], v[194:197], v[122:125]
	v_mfma_f32_16x16x32_bf16 v[118:121], v[170:173], v[194:197], v[118:121]
	v_mfma_f32_16x16x32_bf16 v[114:117], v[186:189], v[194:197], v[114:117]
	ds_read_b128 v[126:129], v0 offset:10240
	s_waitcnt lgkmcnt(2)
	v_mfma_f32_16x16x32_bf16 v[18:21], v[162:165], v[158:161], v[106:109]
	v_mfma_f32_16x16x32_bf16 v[102:105], v[166:169], v[158:161], v[102:105]
	v_mfma_f32_16x16x32_bf16 v[98:101], v[170:173], v[158:161], v[98:101]
	v_mfma_f32_16x16x32_bf16 v[94:97], v[186:189], v[158:161], v[94:97]
	ds_read_b128 v[106:109], v0 offset:12288
	ds_read_b128 v[158:161], v174 offset:32768
	s_waitcnt lgkmcnt(3)
	v_mfma_f32_16x16x32_bf16 v[14:17], v[162:165], v[142:145], v[86:89]
	v_mfma_f32_16x16x32_bf16 v[82:85], v[166:169], v[142:145], v[82:85]
	v_mfma_f32_16x16x32_bf16 v[78:81], v[170:173], v[142:145], v[78:81]
	v_mfma_f32_16x16x32_bf16 v[74:77], v[186:189], v[142:145], v[74:77]
	ds_read_b128 v[86:89], v0 offset:14336
	ds_read_b128 v[142:145], v174 offset:34816
	v_add_u32_e32 v0, v0, v181
	s_waitcnt lgkmcnt(4)
	v_mfma_f32_16x16x32_bf16 v[10:13], v[162:165], v[126:129], v[70:73]
	v_mfma_f32_16x16x32_bf16 v[66:69], v[166:169], v[126:129], v[66:69]
	v_mfma_f32_16x16x32_bf16 v[62:65], v[170:173], v[126:129], v[62:65]
	v_mfma_f32_16x16x32_bf16 v[58:61], v[186:189], v[126:129], v[58:61]
	ds_read_b128 v[70:73], v0 offset:0
	ds_read_b128 v[126:129], v174 offset:36864
	s_waitcnt lgkmcnt(5)
	v_mfma_f32_16x16x32_bf16 v[6:9], v[162:165], v[106:109], v[54:57]
	v_mfma_f32_16x16x32_bf16 v[50:53], v[166:169], v[106:109], v[50:53]
	v_mfma_f32_16x16x32_bf16 v[46:49], v[170:173], v[106:109], v[46:49]
	v_mfma_f32_16x16x32_bf16 v[42:45], v[186:189], v[106:109], v[42:45]
	ds_read_b128 v[106:109], v174 offset:38912
	ds_read_b128 v[54:57], v0 offset:2048
	s_waitcnt lgkmcnt(5)
	v_mfma_f32_16x16x32_bf16 v[2:5], v[162:165], v[86:89], v[38:41]
	v_mfma_f32_16x16x32_bf16 v[34:37], v[166:169], v[86:89], v[34:37]
	v_mfma_f32_16x16x32_bf16 v[38:41], v[170:173], v[86:89], v[90:93]
	v_mfma_f32_16x16x32_bf16 v[86:89], v[186:189], v[86:89], v[110:113]
	s_nop 1
	ds_read_b128 v[90:93], v0 offset:4096
	s_waitcnt lgkmcnt(4)
	v_mfma_f32_16x16x32_bf16 v[30:33], v[158:161], v[70:73], v[30:33]
	v_mfma_f32_16x16x32_bf16 v[110:113], v[142:145], v[70:73], v[154:157]
	s_waitcnt lgkmcnt(3)
; template <int NT, int BM, int BN, bool PLAIN, int NSTAGE, bool EPI_LDS>
; __device__ __forceinline__ void gemm_tile(const Params& p, const GemmDesc& g, bf16_t* lds, const int tid) {
;     ...
;       if (kt + 1 < nk) {
;         const int cur = kt & 1;
;         COMPUTE_X(cur, 1, 0, 0)
;         __syncthreads();
;         ++kt;
;       }
	v_mfma_f32_16x16x32_bf16 v[150:153], v[126:129], v[70:73], v[150:153]
	s_waitcnt lgkmcnt(2)
	v_mfma_f32_16x16x32_bf16 v[70:73], v[106:109], v[70:73], v[146:149]
	s_nop 2
	ds_read_b128 v[146:149], v0 offset:6144
	s_waitcnt lgkmcnt(2)
	v_mfma_f32_16x16x32_bf16 v[26:29], v[158:161], v[54:57], v[26:29]
	v_mfma_f32_16x16x32_bf16 v[138:141], v[142:145], v[54:57], v[138:141]
	v_mfma_f32_16x16x32_bf16 v[134:137], v[126:129], v[54:57], v[134:137]
	v_mfma_f32_16x16x32_bf16 v[54:57], v[106:109], v[54:57], v[130:133]
	s_nop 2
	ds_read_b128 v[130:133], v0 offset:8192
	s_waitcnt lgkmcnt(2)
	v_mfma_f32_16x16x32_bf16 v[22:25], v[158:161], v[90:93], v[22:25]
	v_mfma_f32_16x16x32_bf16 v[122:125], v[142:145], v[90:93], v[122:125]
	v_mfma_f32_16x16x32_bf16 v[118:121], v[126:129], v[90:93], v[118:121]
	v_mfma_f32_16x16x32_bf16 v[90:93], v[106:109], v[90:93], v[114:117]
	s_nop 2
	ds_read_b128 v[114:117], v0 offset:10240
	s_waitcnt lgkmcnt(2)
	v_mfma_f32_16x16x32_bf16 v[18:21], v[158:161], v[146:149], v[18:21]
	v_mfma_f32_16x16x32_bf16 v[102:105], v[142:145], v[146:149], v[102:105]
	v_mfma_f32_16x16x32_bf16 v[98:101], v[126:129], v[146:149], v[98:101]
	v_mfma_f32_16x16x32_bf16 v[94:97], v[106:109], v[146:149], v[94:97]
	ds_read_b128 v[146:149], v0 offset:12288
	s_waitcnt lgkmcnt(2)
	v_mfma_f32_16x16x32_bf16 v[14:17], v[158:161], v[130:133], v[14:17]
	v_mfma_f32_16x16x32_bf16 v[82:85], v[142:145], v[130:133], v[82:85]
	v_mfma_f32_16x16x32_bf16 v[78:81], v[126:129], v[130:133], v[78:81]
	v_mfma_f32_16x16x32_bf16 v[74:77], v[106:109], v[130:133], v[74:77]
	ds_read_b128 v[130:133], v0 offset:14336
	v_or_b32_e32 v0, s3, v180
	v_add_u32_e32 v186, v0, v184
	s_waitcnt lgkmcnt(2)
	v_mfma_f32_16x16x32_bf16 v[10:13], v[158:161], v[114:117], v[10:13]
	s_waitcnt vmcnt(0) lgkmcnt(0)
	s_barrier
; template <int NT, int BM, int BN, bool PLAIN, int NSTAGE, bool EPI_LDS>
; __device__ __forceinline__ void gemm_tile(const Params& p, const GemmDesc& g, bf16_t* lds, const int tid) {
;     ...
;       {
;         const int cur = kt & 1;
;         COMPUTE_X(cur, 0, 0, 0)
;         __syncthreads();
;       }
;     } else {
;       for (int kt = 0; kt < nk; ++kt) {
;         const int cur = kt & 1;
;         if (kt + 1 < nk) {
;           LWRITE(cur ^ 1)
;           if (kt + 2 < nk) GLOAD(kt + 2)
;         }
;         __builtin_amdgcn_sched_barrier(0);
;         COMPUTE(cur)
;         __syncthreads();
;       }
;     }
;   }
;     ...
;   int m0e = m0, n0e = n0;
;   asm volatile("" : "+s"(m0e), "+s"(n0e));
;   if (EPI_LDS) {
;     constexpr int CST = BN + 16;
;     bf16_t* ct = lds;
;     const bool relu2 = (g.epi == E_RELU2);
; #pragma unroll
;     for (int mi = 0; mi < MI; ++mi)
; #pragma unroll
;       for (int ni = 0; ni < NI; ++ni) {
;         f32x4 v = acc[mi][ni];
;         if (relu2) {
; #pragma unroll
;           for (int j = 0; j < 4; ++j) { const float r = fmaxf(v[j], 0.f); v[j] = r * r; }
;         }
;         u32x2 w;
;         w[0] = pack2(v[0], v[1]);
;         w[1] = pack2(v[2], v[3]);
;         *(u32x2*)(ct + (wm * WTM + mi * 16 + fr) * CST + wn * WTN + ni * 16 + fq * 4) = w;
	v_mfma_f32_16x16x32_bf16 v[66:69], v[142:145], v[114:117], v[66:69]
	v_add_u32_e32 v0, v0, v183
	v_mfma_f32_16x16x32_bf16 v[62:65], v[126:129], v[114:117], v[62:65]
	v_mfma_f32_16x16x32_bf16 v[58:61], v[106:109], v[114:117], v[58:61]
	v_mfma_f32_16x16x32_bf16 v[6:9], v[158:161], v[146:149], v[6:9]
	v_mfma_f32_16x16x32_bf16 v[50:53], v[142:145], v[146:149], v[50:53]
	v_mfma_f32_16x16x32_bf16 v[46:49], v[126:129], v[146:149], v[46:49]
	v_mfma_f32_16x16x32_bf16 v[42:45], v[106:109], v[146:149], v[42:45]
	v_mfma_f32_16x16x32_bf16 v[2:5], v[158:161], v[130:133], v[2:5]
	v_mfma_f32_16x16x32_bf16 v[34:37], v[142:145], v[130:133], v[34:37]
	v_mfma_f32_16x16x32_bf16 v[38:41], v[126:129], v[130:133], v[38:41]
	v_mfma_f32_16x16x32_bf16 v[86:89], v[106:109], v[130:133], v[86:89]
	ds_read_b128 v[106:109], v186 offset:32768
	ds_read_b128 v[114:117], v186 offset:34816
	ds_read_b128 v[130:133], v186 offset:36864
	ds_read_b128 v[142:145], v186 offset:38912
	ds_read_b128 v[126:129], v0
	ds_read_b128 v[146:149], v0 offset:2048
	ds_read_b128 v[154:157], v0 offset:4096
	s_waitcnt lgkmcnt(2)
	v_mfma_f32_16x16x32_bf16 v[30:33], v[106:109], v[126:129], v[30:33]
	v_mfma_f32_16x16x32_bf16 v[110:113], v[114:117], v[126:129], v[110:113]
	v_mfma_f32_16x16x32_bf16 v[150:153], v[130:133], v[126:129], v[150:153]
	v_mfma_f32_16x16x32_bf16 v[70:73], v[142:145], v[126:129], v[70:73]
	ds_read_b128 v[126:129], v0 offset:6144
	s_waitcnt lgkmcnt(2)
	v_mfma_f32_16x16x32_bf16 v[26:29], v[106:109], v[146:149], v[26:29]
	v_mfma_f32_16x16x32_bf16 v[138:141], v[114:117], v[146:149], v[138:141]
	v_mfma_f32_16x16x32_bf16 v[134:137], v[130:133], v[146:149], v[134:137]
	v_mfma_f32_16x16x32_bf16 v[54:57], v[142:145], v[146:149], v[54:57]
	ds_read_b128 v[146:149], v0 offset:8192
	s_waitcnt lgkmcnt(2)
	v_mfma_f32_16x16x32_bf16 v[22:25], v[106:109], v[154:157], v[22:25]
	v_mfma_f32_16x16x32_bf16 v[158:161], v[114:117], v[154:157], v[122:125]
	v_mfma_f32_16x16x32_bf16 v[162:165], v[130:133], v[154:157], v[118:121]
	v_mfma_f32_16x16x32_bf16 v[154:157], v[142:145], v[154:157], v[90:93]
	s_nop 2
	ds_read_b128 v[90:93], v0 offset:10240
	s_waitcnt lgkmcnt(2)
	v_mfma_f32_16x16x32_bf16 v[18:21], v[106:109], v[126:129], v[18:21]
	v_mfma_f32_16x16x32_bf16 v[166:169], v[114:117], v[126:129], v[102:105]
	v_mfma_f32_16x16x32_bf16 v[170:173], v[130:133], v[126:129], v[98:101]
	v_mfma_f32_16x16x32_bf16 v[174:177], v[142:145], v[126:129], v[94:97]
	s_nop 1
	v_add_u32_e32 v98, v186, v181
	ds_read_b128 v[186:189], v98 offset:32768
	ds_read_b128 v[94:97], v0 offset:12288
	s_waitcnt lgkmcnt(3)
	v_mfma_f32_16x16x32_bf16 v[14:17], v[106:109], v[146:149], v[14:17]
	v_mfma_f32_16x16x32_bf16 v[190:193], v[114:117], v[146:149], v[82:85]
	v_mfma_f32_16x16x32_bf16 v[194:197], v[130:133], v[146:149], v[78:81]
	v_mfma_f32_16x16x32_bf16 v[146:149], v[142:145], v[146:149], v[74:77]
	ds_read_b128 v[198:201], v98 offset:34816
	s_nop 1
	ds_read_b128 v[74:77], v0 offset:14336
	v_add_u32_e32 v0, v0, v181
	s_waitcnt lgkmcnt(4)
	v_mfma_f32_16x16x32_bf16 v[10:13], v[106:109], v[90:93], v[10:13]
	v_mfma_f32_16x16x32_bf16 v[202:205], v[114:117], v[90:93], v[66:69]
	v_mfma_f32_16x16x32_bf16 v[206:209], v[130:133], v[90:93], v[62:65]
	v_mfma_f32_16x16x32_bf16 v[226:229], v[142:145], v[90:93], v[58:61]
	ds_read_b128 v[230:233], v98 offset:36864
	s_nop 1
	ds_read_b128 v[58:61], v0 offset:0
	s_waitcnt lgkmcnt(4)
	v_mfma_f32_16x16x32_bf16 v[6:9], v[106:109], v[94:97], v[6:9]
	v_mfma_f32_16x16x32_bf16 v[234:237], v[114:117], v[94:97], v[50:53]
	v_mfma_f32_16x16x32_bf16 v[238:241], v[130:133], v[94:97], v[46:49]
	v_mfma_f32_16x16x32_bf16 v[242:245], v[142:145], v[94:97], v[42:45]
	ds_read_b128 v[246:249], v98 offset:38912
	s_nop 1
	ds_read_b128 v[42:45], v0 offset:2048
	s_waitcnt lgkmcnt(4)
	v_mfma_f32_16x16x32_bf16 v[2:5], v[106:109], v[74:77], v[2:5]
	v_mfma_f32_16x16x32_bf16 v[218:221], v[114:117], v[74:77], v[34:37]
	v_mfma_f32_16x16x32_bf16 v[130:133], v[130:133], v[74:77], v[38:41]
	v_mfma_f32_16x16x32_bf16 v[142:145], v[142:145], v[74:77], v[86:89]
	s_nop 0
	ds_read_b128 v[34:37], v0 offset:4096
	s_waitcnt lgkmcnt(3)
	v_mfma_f32_16x16x32_bf16 v[126:129], v[186:189], v[58:61], v[30:33]
	v_mfma_f32_16x16x32_bf16 v[122:125], v[198:201], v[58:61], v[110:113]
	v_mfma_f32_16x16x32_bf16 v[118:121], v[230:233], v[58:61], v[150:153]
	s_waitcnt lgkmcnt(2)
	v_mfma_f32_16x16x32_bf16 v[114:117], v[246:249], v[58:61], v[70:73]
	ds_read_b128 v[30:33], v0 offset:6144
	s_waitcnt lgkmcnt(2)
	v_mfma_f32_16x16x32_bf16 v[110:113], v[186:189], v[42:45], v[26:29]
	v_mfma_f32_16x16x32_bf16 v[106:109], v[198:201], v[42:45], v[138:141]
	v_mfma_f32_16x16x32_bf16 v[102:105], v[230:233], v[42:45], v[134:137]
	v_mfma_f32_16x16x32_bf16 v[98:101], v[246:249], v[42:45], v[54:57]
	ds_read_b128 v[26:29], v0 offset:8192
	s_waitcnt lgkmcnt(2)
	v_mfma_f32_16x16x32_bf16 v[94:97], v[186:189], v[34:37], v[22:25]
	v_mfma_f32_16x16x32_bf16 v[90:93], v[198:201], v[34:37], v[158:161]
	v_mfma_f32_16x16x32_bf16 v[86:89], v[230:233], v[34:37], v[162:165]
	v_mfma_f32_16x16x32_bf16 v[82:85], v[246:249], v[34:37], v[154:157]
	ds_read_b128 v[22:25], v0 offset:10240
	s_waitcnt lgkmcnt(2)
	v_mfma_f32_16x16x32_bf16 v[78:81], v[186:189], v[30:33], v[18:21]
	v_mfma_f32_16x16x32_bf16 v[74:77], v[198:201], v[30:33], v[166:169]
	v_mfma_f32_16x16x32_bf16 v[70:73], v[230:233], v[30:33], v[170:173]
	v_mfma_f32_16x16x32_bf16 v[66:69], v[246:249], v[30:33], v[174:177]
	ds_read_b128 v[18:21], v0 offset:12288
	s_waitcnt lgkmcnt(2)
	v_mfma_f32_16x16x32_bf16 v[62:65], v[186:189], v[26:29], v[14:17]
	v_mfma_f32_16x16x32_bf16 v[58:61], v[198:201], v[26:29], v[190:193]
	v_mfma_f32_16x16x32_bf16 v[54:57], v[230:233], v[26:29], v[194:197]
	v_mfma_f32_16x16x32_bf16 v[50:53], v[246:249], v[26:29], v[146:149]
	ds_read_b128 v[134:137], v0 offset:14336
	s_waitcnt lgkmcnt(0)
	s_barrier
	v_mfma_f32_16x16x32_bf16 v[46:49], v[186:189], v[22:25], v[10:13]
	v_mfma_f32_16x16x32_bf16 v[42:45], v[198:201], v[22:25], v[202:205]
	v_mfma_f32_16x16x32_bf16 v[38:41], v[230:233], v[22:25], v[206:209]
	v_mfma_f32_16x16x32_bf16 v[34:37], v[246:249], v[22:25], v[226:229]
	v_mfma_f32_16x16x32_bf16 v[30:33], v[186:189], v[18:21], v[6:9]
	v_mfma_f32_16x16x32_bf16 v[26:29], v[198:201], v[18:21], v[234:237]
	v_mfma_f32_16x16x32_bf16 v[22:25], v[230:233], v[18:21], v[238:241]
	v_mfma_f32_16x16x32_bf16 v[18:21], v[246:249], v[18:21], v[242:245]
	v_mfma_f32_16x16x32_bf16 v[14:17], v[186:189], v[134:137], v[2:5]
	v_mfma_f32_16x16x32_bf16 v[10:13], v[198:201], v[134:137], v[218:221]
	v_mfma_f32_16x16x32_bf16 v[2:5], v[230:233], v[134:137], v[130:133]
	v_mfma_f32_16x16x32_bf16 v[6:9], v[246:249], v[134:137], v[142:145]
	s_cbranch_vccz .LBB0_900
	s_nop 0
	v_cvt_pk_bf16_f32 v130, v126, v127
	v_cvt_pk_bf16_f32 v131, v128, v129
	s_mov_b64 s[28:29], 0
